# q/kv up-projection GEMM: skip the K-tiles whose weights are structurally zero (4 of 6 K-tiles per tile)
# speedup vs baseline: 1.0224x; 1.0058x over previous
.LBB0_183:
	s_and_b64 vcc, exec, s[2:3]
	s_cbranch_vccz .LBB0_290
	s_cmpk_gt_i32 s20, 0x7f
	s_mov_b64 s[2:3], -1
	s_cbranch_scc0 .LBB0_277
	s_waitcnt vmcnt(2)
	v_bfe_i32 v2, v160, 27, 1
	v_lshlrev_b32_e32 v0, 4, v160
	v_lshrrev_b32_e32 v2, 22, v2
	v_add_u32_e32 v2, v0, v2
	v_and_b32_e32 v2, 0xfffffc00, v2
	v_sub_u32_e32 v2, v0, v2
	v_ashrrev_i32_e32 v1, 31, v160
	v_lshrrev_b32_e32 v3, 4, v2
	v_lshrrev_b32_e32 v1, 26, v1
	v_bitop3_b32 v2, v3, v2, 32 bitop3:0x6c
	v_add_u32_e32 v1, v160, v1
	s_waitcnt vmcnt(1)
	v_ashrrev_i32_e32 v4, 31, v2
	v_ashrrev_i32_e32 v1, 6, v1
	v_lshrrev_b32_e32 v4, 26, v4
	v_lshlrev_b32_e32 v3, 3, v1
	v_add_u32_e32 v4, v2, v4
	v_lshlrev_b32_e32 v1, 5, v1
	v_and_b32_e32 v133, 32, v1
	v_and_b32_e32 v1, 0xc0, v4
	v_sub_u32_e32 v1, v2, v1
	v_ashrrev_i16_sdwa v1, v196, sext(v1) dst_sel:DWORD dst_unused:UNUSED_PAD src0_sel:DWORD src1_sel:BYTE_0
	v_add_u32_e32 v0, 0x2000, v0
	v_bfe_i32 v146, v1, 0, 16
	v_ashrrev_i32_e32 v1, 31, v0
	v_lshrrev_b32_e32 v1, 22, v1
	v_add_u32_e32 v1, v0, v1
	v_ashrrev_i32_e32 v1, 10, v1
	v_mul_i32_i24_e32 v2, 0x400, v1
	v_sub_u32_e32 v0, v0, v2
	v_lshrrev_b32_e32 v2, 4, v0
	v_and_b32_e32 v3, 0x7ffffff0, v3
	v_ashrrev_i32_e32 v5, 6, v4
	v_bitop3_b32 v2, v2, v0, 32 bitop3:0x6c
	v_add_u32_e32 v150, v5, v3
	v_ashrrev_i32_e32 v3, 31, v2
	v_lshrrev_b32_e32 v3, 26, v3
	v_lshlrev_b32_e32 v0, 3, v1
	v_add_u32_e32 v3, v2, v3
	v_and_b32_e32 v0, 0x7ffffff0, v0
	v_ashrrev_i32_e32 v4, 6, v3
	v_add_u32_e32 v152, v4, v0
	v_lshlrev_b32_e32 v0, 5, v1
	v_and_b32_e32 v1, 0xc0, v3
	v_sub_u32_e32 v1, v2, v1
	s_add_i32 s53, s20, 0xffffff80
	s_movk_i32 s40, 0x180
	v_ashrrev_i16_sdwa v1, v196, sext(v1) dst_sel:DWORD dst_unused:UNUSED_PAD src0_sel:DWORD src1_sel:BYTE_0
	v_and_b32_e32 v149, 15, v160
	v_bfe_u32 v141, v160, 4, 2
	v_lshlrev_b32_e32 v3, 2, v160
	v_and_b32_e32 v0, 32, v0
	v_bfe_i32 v1, v1, 0, 16
	v_lshlrev_b32_e32 v147, 4, v141
	v_lshlrev_b32_e32 v2, 6, v149
	v_and_b32_e32 v3, 32, v3
	s_cmpk_lt_u32 s53, 0x220
	v_readfirstlane_b32 s9, v160
	v_add_u32_e32 v151, v133, v146
	v_add_u32_e32 v153, v0, v1
	s_cselect_b64 s[2:3], -1, 0
	s_cmpk_gt_u32 s53, 0x21f
	v_bitop3_b32 v148, v147, v3, v2 bitop3:0x36
	s_cbranch_scc1 .LBB0_266
	v_readlane_b32 s6, v255, 6
	v_readlane_b32 s7, v255, 7
	s_add_u32 s34, s6, 0x1400000
	s_addc_u32 s35, s7, 0
	s_ashr_i32 s10, s9, 6
	s_ashr_i32 s41, s40, 31
	v_writelane_b32 v255, s9, 17
	s_ashr_i32 s9, s9, 8
	s_lshl_b64 s[88:89], s[40:41], 8
	s_lshl_b64 s[62:63], s[40:41], 9
	s_lshl_b32 s54, s10, 10
	s_and_b64 s[2:3], s[2:3], exec
	s_cselect_b32 s2, s53, 0
	s_and_b32 s3, s2, 7
	s_mulk_i32 s3, 0x44
	s_lshr_b32 s2, s2, 3
	s_add_i32 s3, s3, s2
	s_lshr_b32 s2, s3, 2
	s_and_b32 s6, s2, 0xffc
	s_sub_i32 s2, 0x88, s6
	s_min_u32 s7, s2, 4
	v_cvt_f32_ubyte0_e32 v3, s7
	v_rcp_iflag_f32_e32 v4, v3
	s_and_b32 s19, s3, 15
	v_cvt_f32_ubyte0_e32 v2, s19
	v_writelane_b32 v255, s34, 18
	v_mul_f32_e32 v4, v2, v4
	v_trunc_f32_e32 v4, v4
	v_fma_f32 v2, -v4, v3, v2
	v_cvt_u32_f32_e32 v4, v4
	v_cmp_ge_f32_e64 s[2:3], |v2|, v3
	s_cmp_lg_u64 s[2:3], 0
	v_mul_lo_u32 v2, s40, v150
	v_readfirstlane_b32 s21, v4
	s_addc_u32 s21, s21, 0
	s_mul_i32 s2, s21, s7
	s_sub_i32 s2, s19, s2
	s_and_b32 s2, s2, 0xff
	s_add_i32 s24, s6, s2
	s_add_u32 s38, s26, 0xb860000
	s_addc_u32 s39, s27, 0
	s_lshr_b64 s[2:3], s[40:41], 23
	s_mul_i32 s3, s2, s24
	s_mul_hi_u32 s6, s62, s24
	s_and_b32 s25, s21, 0xff
	s_add_i32 s3, s6, s3
	s_mul_i32 s2, s2, s25
	s_mul_hi_u32 s6, s62, s25
	s_add_i32 s2, s6, s2
	s_mul_i32 s6, s62, s25
	s_add_u32 s6, s34, s6
	s_addc_u32 s7, s35, s2
	s_cmp_gt_u32 s25, 1
	s_cselect_b32 s19, 0x100, 0
	s_add_u32 s6, s6, s19
	s_addc_u32 s7, s7, 0
	s_add_i32 s79, s54, 0
	v_add_lshl_u32 v130, v2, v151, 1
	s_add_i32 m0, s79, 0x10000
	v_mul_lo_u32 v3, s40, v152
	s_mul_i32 s19, s62, s24
	v_writelane_b32 v255, s35, 19
	global_load_lds_dwordx4 v130, s[6:7]
	s_add_i32 m0, s79, 0x12000
	v_add_lshl_u32 v128, v3, v153, 1
	v_writelane_b32 v255, s38, 20
	s_add_u32 s38, s38, s19
	global_load_lds_dwordx4 v128, s[6:7]
	s_mov_b32 s74, s39
	s_addc_u32 s39, s39, s3
	s_cmp_gt_u32 s25, 1
	s_cselect_b32 s3, 0x100, 0
	s_add_u32 s38, s38, s3
	s_addc_u32 s39, s39, 0
	s_mov_b32 m0, s79
	s_add_i32 s34, s79, 0x2000
	global_load_lds_dwordx4 v130, s[38:39]
	s_mov_b32 m0, s34
	s_add_u32 s2, s6, s88
	global_load_lds_dwordx4 v128, s[38:39]
	s_addc_u32 s3, s7, s89
	s_add_i32 m0, s79, 0x14000
	s_movk_i32 s77, 0x2200
	global_load_lds_dwordx4 v130, s[2:3]
	s_add_i32 m0, s79, 0x16000
	s_add_u32 s42, s38, s88
	s_addc_u32 s43, s39, s89
	s_add_i32 s35, s79, 0x4000
	global_load_lds_dwordx4 v128, s[2:3]
	s_mov_b32 m0, s35
	s_add_i32 s44, s79, 0x6000
	global_load_lds_dwordx4 v130, s[42:43]
	s_mov_b32 m0, s44
	s_cmp_lg_u32 s9, 1
	global_load_lds_dwordx4 v128, s[42:43]
	s_cbranch_scc1 .LBB0_188
	s_barrier
.LBB0_188:
	v_mov_b32_e32 v131, v157
	v_lshl_add_u64 v[4:5], s[6:7], 0, v[130:131]
	v_mov_b32_e32 v129, v157
	v_lshl_add_u64 v[6:7], s[6:7], 0, v[128:129]
	s_add_i32 m0, s79, 0x18000
	v_lshl_add_u64 v[4:5], v[4:5], 0, s[50:51]
	v_lshl_add_u64 v[8:9], s[38:39], 0, v[130:131]
	s_waitcnt vmcnt(4)
	s_barrier
	global_load_lds_dwordx4 v[4:5], off
	v_lshl_add_u64 v[4:5], v[6:7], 0, s[50:51]
	s_add_i32 m0, s79, 0x1a000
	s_add_i32 s82, s79, 0x8000
	v_lshl_add_u64 v[10:11], s[38:39], 0, v[128:129]
	global_load_lds_dwordx4 v[4:5], off
	v_lshl_add_u64 v[4:5], v[8:9], 0, s[50:51]
	s_mov_b32 m0, s82
	s_add_i32 s83, s79, 0xa000
	v_lshl_add_u64 v[12:13], s[2:3], 0, v[130:131]
	global_load_lds_dwordx4 v[4:5], off
	v_lshl_add_u64 v[4:5], v[10:11], 0, s[50:51]
	s_mov_b32 m0, s83
	v_lshl_add_u64 v[14:15], s[2:3], 0, v[128:129]
	global_load_lds_dwordx4 v[4:5], off
	s_add_i32 m0, s79, 0x1c000
	v_lshl_add_u64 v[4:5], v[12:13], 0, s[50:51]
	global_load_lds_dwordx4 v[4:5], off
	v_lshl_add_u64 v[4:5], v[14:15], 0, s[50:51]
	s_add_i32 m0, s79, 0x1e000
	s_lshr_b32 s2, s41, 26
	global_load_lds_dwordx4 v[4:5], off
	s_add_i32 s2, s40, s2
	s_ashr_i32 s66, s2, 6
	s_mov_b32 s66, 4
	s_and_b32 s2, s10, 3
	s_lshl_b32 s3, s9, 6
	s_add_i32 s45, s18, 0xffffff80
	v_writelane_b32 v255, s3, 21
	s_lshl_b32 s3, s9, 13
	s_lshl_b32 s19, s2, 5
	v_lshlrev_b32_e32 v17, 2, v149
	s_cmp_eq_u32 s2, 3
	v_lshl_or_b32 v16, v149, 6, v147
	v_and_b32_e32 v17, 32, v17
	s_cselect_b64 s[84:85], -1, 0
	s_cmp_lt_u32 s2, 2
	v_bitop3_b32 v16, v16, s3, v17 bitop3:0xde
	v_lshl_or_b32 v154, s2, 12, v148
	s_cselect_b64 s[2:3], -1, 0
	v_writelane_b32 v255, s2, 22
	v_add_u32_e32 v0, v3, v0
	s_waitcnt vmcnt(6)
	v_add_lshl_u32 v156, v0, v1, 1
	v_writelane_b32 v255, s3, 23
	s_sub_i32 s2, s19, 64
	v_add_u32_e32 v0, v2, v133
	v_lshlrev_b32_e32 v132, 2, v141
	s_cmp_gt_i32 s40, 63
	v_lshl_add_u64 v[136:137], s[88:89], 0, v[156:157]
	v_add_lshl_u32 v156, v0, v146, 1
	v_or_b32_e32 v134, s2, v132
	v_mov_b32_e32 v135, v157
	s_cselect_b64 s[80:81], -1, 0
	s_add_i32 s9, s66, -2
	v_lshl_add_u64 v[138:139], s[88:89], 0, v[156:157]
	s_mov_b32 s67, 0
	v_add_u32_e32 v155, 0, v16
	s_mov_b64 s[68:69], s[38:39]
	s_barrier
	s_branch .LBB0_191

.LBB0_191:
	s_add_i32 s67, s67, 1
	s_mul_i32 s2, s67, s45
	s_add_i32 s10, s2, s53
	s_cmpk_gt_i32 s10, 0x21f
	s_cselect_b64 s[96:97], -1, 0
	s_cmpk_lt_i32 s10, 0x220
	s_cselect_b64 s[2:3], -1, 0
	s_and_b64 s[40:41], s[2:3], exec
	s_cselect_b32 s10, s10, 0
	s_ashr_i32 s21, s10, 31
	s_lshr_b32 s21, s21, 29
	s_add_i32 s21, s10, s21
	s_ashr_i32 s40, s21, 3
	s_and_b32 s21, s21, -8
	s_sub_i32 s10, s10, s21
	s_cmp_lt_i32 s10, 0
	s_movk_i32 s21, 0x45
	s_cselect_b32 s21, s21, 0x44
	s_mul_i32 s10, s21, s10
	s_add_i32 s10, s10, s40
	s_ashr_i32 s21, s10, 31
	s_lshr_b32 s21, s21, 28
	s_add_i32 s21, s10, s21
	s_ashr_i32 s40, s21, 4
	s_lshl_b32 s78, s40, 2
	s_sub_i32 s40, 0x88, s78
	s_min_u32 s42, s40, 4
	s_and_b32 s21, s21, -16
	s_sub_i32 s10, s10, s21
	v_cvt_f32_ubyte0_e32 v1, s42
	v_cvt_f32_i32_e32 v0, s10
	v_rcp_iflag_f32_e32 v2, v1
	s_ashr_i32 s21, s10, 30
	s_or_b32 s21, s21, 1
	v_mul_f32_e32 v2, v0, v2
	v_trunc_f32_e32 v2, v2
	v_fma_f32 v0, -v2, v1, v0
	v_cvt_i32_f32_e32 v2, v2
	v_cmp_ge_f32_e64 s[40:41], |v0|, v1
	s_and_b64 s[40:41], s[40:41], exec
	s_cselect_b32 s21, s21, 0
	v_readfirstlane_b32 s55, v2
	s_add_i32 s55, s55, s21
	s_mul_i32 s21, s55, s42
	s_sub_i32 s10, s10, s21
	s_sext_i32_i8 s10, s10
	s_add_i32 s78, s78, s10
	s_and_b64 vcc, exec, s[96:97]
	s_cbranch_vccnz .LBB0_193
	s_ashr_i32 s10, s78, 31
	s_mul_hi_u32 s21, s62, s78
	s_mul_i32 s10, s62, s10
	s_add_i32 s10, s21, s10
	s_mul_i32 s21, s63, s78
	s_add_i32 s10, s10, s21
	s_mul_i32 s21, s62, s78
	v_readlane_b32 s40, v255, 20
	s_add_u32 s68, s40, s21
	s_addc_u32 s69, s74, s10
	s_and_b32 s10, s55, 0xff
	s_cmp_gt_u32 s10, 1
	s_cselect_b32 s10, 0x100, 0
	s_add_u32 s68, s68, s10
	s_addc_u32 s69, s69, 0
.LBB0_193:
	s_andn2_b64 vcc, exec, s[2:3]
	s_mov_b64 s[94:95], s[6:7]
	s_cbranch_vccnz .LBB0_195
	v_mov_b32_e32 v0, s55
	s_nop 0
	v_readfirstlane_b32 s10, v0
	s_bfe_i64 s[2:3], s[10:11], 0x80000
	s_mul_i32 s3, s62, s3
	s_mul_hi_u32 s10, s62, s2
	s_add_i32 s3, s10, s3
	s_mul_i32 s10, s63, s2
	s_add_i32 s3, s3, s10
	s_mul_i32 s2, s62, s2
	v_readlane_b32 s10, v255, 18
	s_add_u32 s94, s10, s2
	v_readlane_b32 s2, v255, 19
	s_addc_u32 s95, s2, s3
	s_and_b32 s2, s55, 0xff
	s_cmp_gt_u32 s2, 1
	s_cselect_b32 s2, 0x100, 0
	s_add_u32 s94, s94, s2
	s_addc_u32 s95, s95, 0
